# attention sample loop: K and V fragment ds_reads issued 8-deep with counted lgkmcnt (was read-wait-mfma per fragment)
# speedup vs baseline: 1.0119x; 1.0023x over previous
.LBB0_1100:
	global_load_dwordx4 v[90:93], v[82:83], off offset:16
	global_load_dwordx4 v[94:97], v[82:83], off
	s_nop 0
	global_load_dwordx4 v[82:85], v[86:87], off offset:16
	s_nop 0
	global_load_dwordx4 v[86:89], v[86:87], off
	v_add_u32_e32 v1, v151, v153
	ds_read_b128 v[208:211], v1
	ds_read_b128 v[212:215], v1 offset:64
	ds_read_b128 v[216:219], v157
	ds_read_b128 v[220:223], v157 offset:64
	ds_read_b128 v[224:227], v154
	ds_read_b128 v[228:231], v154 offset:64
	ds_read_b128 v[244:247], v152
	ds_read_b128 v[248:251], v152 offset:64
	s_waitcnt lgkmcnt(7)
	v_mfma_f32_16x16x32_bf16 v[106:109], v[208:211], v[66:69], 0
	v_mfma_f32_16x16x32_bf16 v[98:101], v[208:211], v[74:77], 0
	s_waitcnt lgkmcnt(6)
	v_mfma_f32_16x16x32_bf16 v[118:121], v[212:215], v[70:73], v[106:109]
	v_mfma_f32_16x16x32_bf16 v[106:109], v[212:215], v[78:81], v[98:101]
	s_waitcnt lgkmcnt(5)
	v_mfma_f32_16x16x32_bf16 v[98:101], v[216:219], v[66:69], 0
	v_mfma_f32_16x16x32_bf16 v[102:105], v[216:219], v[74:77], 0
	s_waitcnt lgkmcnt(4)
	v_mfma_f32_16x16x32_bf16 v[98:101], v[220:223], v[70:73], v[98:101]
	v_mfma_f32_16x16x32_bf16 v[102:105], v[220:223], v[78:81], v[102:105]
	s_waitcnt lgkmcnt(3)
	v_mfma_f32_16x16x32_bf16 v[122:125], v[224:227], v[66:69], 0
	v_mfma_f32_16x16x32_bf16 v[110:113], v[224:227], v[74:77], 0
	s_waitcnt lgkmcnt(2)
	v_mfma_f32_16x16x32_bf16 v[122:125], v[228:231], v[70:73], v[122:125]
	v_mfma_f32_16x16x32_bf16 v[110:113], v[228:231], v[78:81], v[110:113]
	s_waitcnt lgkmcnt(1)
	v_mfma_f32_16x16x32_bf16 v[126:129], v[244:247], v[66:69], 0
	v_mfma_f32_16x16x32_bf16 v[114:117], v[244:247], v[74:77], 0
	s_waitcnt lgkmcnt(0)
	v_mfma_f32_16x16x32_bf16 v[126:129], v[248:251], v[70:73], v[126:129]
	v_mfma_f32_16x16x32_bf16 v[114:117], v[248:251], v[78:81], v[114:117]
	ds_read_b128 v[208:211], v131 offset:17408
	ds_read_b128 v[212:215], v131 offset:19712
	ds_read_b128 v[216:219], v131 offset:22016
	ds_read_b128 v[220:223], v131 offset:24320
	ds_read_b128 v[224:227], v131 offset:26624
	ds_read_b128 v[228:231], v131 offset:28928
	ds_read_b128 v[244:247], v131 offset:31232
	ds_read_b128 v[248:251], v131 offset:33536
	v_max3_f32 v136, v118, s88, v119
	v_max3_f32 v136, v136, v120, v121
	v_max3_f32 v175, v106, s88, v107
	v_max3_f32 v175, v175, v108, v109
	v_max3_f32 v136, v136, v98, v99
	v_max3_f32 v136, v136, v100, v101
	v_max3_f32 v175, v175, v102, v103
	v_max3_f32 v175, v175, v104, v105
	v_max3_f32 v136, v136, v122, v123
	v_max3_f32 v136, v136, v124, v125
	v_max3_f32 v175, v175, v110, v111
	v_max3_f32 v175, v175, v112, v113
	v_max3_f32 v136, v136, v126, v127
	v_max3_f32 v175, v175, v114, v115
	v_max3_f32 v136, v136, v128, v129
	v_max3_f32 v175, v175, v116, v117
	v_mov_b32_e32 v137, v136
	v_mov_b32_e32 v176, v175
	s_nop 0
	v_permlane16_swap_b32_e32 v136, v137
	v_permlane16_swap_b32_e32 v175, v176
	v_max_f32_e32 v137, v137, v137
	v_max_f32_e32 v136, v136, v136
	v_max_f32_e32 v176, v176, v176
	v_max_f32_e32 v175, v175, v175
	v_max_f32_e32 v136, v136, v137
	v_max_f32_e32 v175, v175, v176
	v_mov_b32_e32 v137, v136
	v_mov_b32_e32 v176, v175
	s_nop 0
	v_permlane32_swap_b32_e32 v136, v137
	v_permlane32_swap_b32_e32 v175, v176
	v_max_f32_e32 v137, v137, v137
	v_max_f32_e32 v136, v136, v136
	v_max_f32_e32 v176, v176, v176
	v_max_f32_e32 v175, v175, v175
	v_max_f32_e32 v143, v136, v137
	v_pk_add_f32 v[136:137], v[144:145], s[36:37] op_sel_hi:[1,0]
	v_max_f32_e32 v175, v175, v176
	v_cmp_gt_f32_e32 vcc, v175, v136
	v_cmp_gt_f32_e64 s[4:5], v143, v137
	s_nop 0
	v_cndmask_b32_e32 v136, v144, v175, vcc
	v_cndmask_b32_e64 v137, v145, v143, s[4:5]
	v_cmp_neq_f32_e32 vcc, v137, v145
	v_cmp_neq_f32_e64 s[4:5], v136, v144
	s_or_b64 vcc, vcc, s[4:5]
	s_cbranch_vccz .LBB0_1102
	v_pk_add_f32 v[144:145], v[144:145], v[136:137] neg_lo:[0,1] neg_hi:[0,1]
	s_nop 0
	v_exp_f32_e32 v176, v145
	v_exp_f32_e32 v144, v144
	v_mov_b32_e32 v145, v176
	v_pk_mul_f32 v[28:29], v[28:29], v[176:177] op_sel_hi:[1,0]
	v_pk_mul_f32 v[26:27], v[26:27], v[176:177] op_sel_hi:[1,0]
	v_pk_mul_f32 v[8:9], v[8:9], v[176:177] op_sel_hi:[1,0]
	v_pk_mul_f32 v[6:7], v[6:7], v[176:177] op_sel_hi:[1,0]
	v_pk_mul_f32 v[16:17], v[16:17], v[176:177] op_sel_hi:[1,0]
	v_pk_mul_f32 v[14:15], v[14:15], v[176:177] op_sel_hi:[1,0]
	v_pk_mul_f32 v[32:33], v[32:33], v[176:177] op_sel_hi:[1,0]
	v_pk_mul_f32 v[30:31], v[30:31], v[176:177] op_sel_hi:[1,0]
	v_pk_mul_f32 v[40:41], v[40:41], v[176:177] op_sel_hi:[1,0]
	v_pk_mul_f32 v[38:39], v[38:39], v[176:177] op_sel_hi:[1,0]
	v_pk_mul_f32 v[48:49], v[48:49], v[176:177] op_sel_hi:[1,0]
	v_pk_mul_f32 v[46:47], v[46:47], v[176:177] op_sel_hi:[1,0]
	v_pk_mul_f32 v[56:57], v[56:57], v[176:177] op_sel_hi:[1,0]
	v_pk_mul_f32 v[54:55], v[54:55], v[176:177] op_sel_hi:[1,0]
	v_pk_mul_f32 v[64:65], v[64:65], v[176:177] op_sel_hi:[1,0]
	v_pk_mul_f32 v[62:63], v[62:63], v[176:177] op_sel_hi:[1,0]
	v_pk_mul_f32 v[132:133], v[132:133], v[144:145]
	v_pk_mul_f32 v[20:21], v[20:21], v[144:145] op_sel_hi:[1,0]
	v_pk_mul_f32 v[18:19], v[18:19], v[144:145] op_sel_hi:[1,0]
	v_pk_mul_f32 v[4:5], v[4:5], v[144:145] op_sel_hi:[1,0]
	v_pk_mul_f32 v[2:3], v[2:3], v[144:145] op_sel_hi:[1,0]
	v_pk_mul_f32 v[12:13], v[12:13], v[144:145] op_sel_hi:[1,0]
	v_pk_mul_f32 v[10:11], v[10:11], v[144:145] op_sel_hi:[1,0]
	v_pk_mul_f32 v[24:25], v[24:25], v[144:145] op_sel_hi:[1,0]
	v_pk_mul_f32 v[22:23], v[22:23], v[144:145] op_sel_hi:[1,0]
	v_pk_mul_f32 v[36:37], v[36:37], v[144:145] op_sel_hi:[1,0]
	v_pk_mul_f32 v[34:35], v[34:35], v[144:145] op_sel_hi:[1,0]
	v_pk_mul_f32 v[44:45], v[44:45], v[144:145] op_sel_hi:[1,0]
	v_pk_mul_f32 v[42:43], v[42:43], v[144:145] op_sel_hi:[1,0]
	v_pk_mul_f32 v[52:53], v[52:53], v[144:145] op_sel_hi:[1,0]
	v_pk_mul_f32 v[50:51], v[50:51], v[144:145] op_sel_hi:[1,0]
	v_pk_mul_f32 v[60:61], v[60:61], v[144:145] op_sel_hi:[1,0]
	v_pk_mul_f32 v[58:59], v[58:59], v[144:145] op_sel_hi:[1,0]
	v_mov_b64_e32 v[144:145], v[136:137]
	s_branch .LBB0_1103

.LBB0_1103:
	v_sub_f32_e32 v118, v118, v137
	v_sub_f32_e32 v106, v106, v136
	v_exp_f32_e32 v177, v118
	v_sub_f32_e32 v118, v119, v137
	v_exp_f32_e32 v176, v106
	v_sub_f32_e32 v106, v107, v136
	v_exp_f32_e32 v185, v118
	v_sub_f32_e32 v118, v120, v137
	v_exp_f32_e32 v184, v106
	v_sub_f32_e32 v106, v108, v136
	v_exp_f32_e32 v187, v118
	v_sub_f32_e32 v118, v121, v137
	v_exp_f32_e32 v186, v106
	v_sub_f32_e32 v106, v109, v136
	v_sub_f32_e32 v102, v102, v136
	v_exp_f32_e32 v191, v118
	v_sub_f32_e32 v98, v98, v137
	v_exp_f32_e32 v190, v106
	v_exp_f32_e32 v192, v102
	v_sub_f32_e32 v102, v103, v136
	v_exp_f32_e32 v193, v98
	v_sub_f32_e32 v98, v99, v137
	v_exp_f32_e32 v194, v102
	v_pk_add_f32 v[102:103], v[176:177], 0 op_sel_hi:[1,0]
	v_exp_f32_e32 v195, v98
	v_pk_add_f32 v[102:103], v[184:185], v[102:103]
	v_cvt_pk_bf16_f32 v118, v177, v185
	v_pk_add_f32 v[102:103], v[186:187], v[102:103]
	v_sub_f32_e32 v98, v100, v137
	v_pk_add_f32 v[102:103], v[190:191], v[102:103]
	v_cvt_pk_bf16_f32 v106, v176, v184
	v_pk_add_f32 v[102:103], v[192:193], v[102:103]
	v_exp_f32_e32 v197, v98
	v_pk_add_f32 v[176:177], v[194:195], v[102:103]
	v_sub_f32_e32 v102, v104, v136
	v_sub_f32_e32 v98, v101, v137
	v_exp_f32_e32 v196, v102
	v_sub_f32_e32 v102, v105, v136
	v_sub_f32_e32 v104, v114, v136
	v_exp_f32_e32 v199, v98
	v_sub_f32_e32 v98, v122, v137
	v_exp_f32_e32 v198, v102
	v_sub_f32_e32 v102, v110, v136
	v_exp_f32_e32 v204, v104
	v_sub_f32_e32 v104, v115, v136
	v_exp_f32_e32 v201, v98
	v_sub_f32_e32 v98, v123, v137
	v_sub_f32_e32 v100, v126, v137
	v_exp_f32_e32 v200, v102
	v_sub_f32_e32 v102, v111, v136
	v_exp_f32_e32 v126, v104
	v_sub_f32_e32 v104, v116, v136
	v_exp_f32_e32 v123, v98
	v_sub_f32_e32 v98, v124, v137
	v_exp_f32_e32 v205, v100
	v_sub_f32_e32 v100, v127, v137
	v_exp_f32_e32 v122, v102
	v_sub_f32_e32 v102, v112, v136
	v_exp_f32_e32 v206, v104
	v_sub_f32_e32 v104, v117, v136
	v_exp_f32_e32 v203, v98
	v_sub_f32_e32 v98, v125, v137
	v_exp_f32_e32 v127, v100
	v_sub_f32_e32 v100, v128, v137
	v_exp_f32_e32 v202, v102
	v_sub_f32_e32 v102, v113, v136
	v_exp_f32_e32 v128, v104
	v_pk_add_f32 v[104:105], v[196:197], v[176:177]
	v_exp_f32_e32 v125, v98
	v_exp_f32_e32 v124, v102
	v_pk_add_f32 v[104:105], v[198:199], v[104:105]
	v_exp_f32_e32 v207, v100
	v_pk_add_f32 v[104:105], v[200:201], v[104:105]
	v_sub_f32_e32 v100, v129, v137
	v_pk_add_f32 v[104:105], v[122:123], v[104:105]
	v_exp_f32_e32 v129, v100
	v_pk_add_f32 v[104:105], v[202:203], v[104:105]
	v_cvt_pk_bf16_f32 v119, v187, v191
	v_pk_add_f32 v[104:105], v[124:125], v[104:105]
	v_cvt_pk_bf16_f32 v120, v193, v195
	v_pk_add_f32 v[104:105], v[204:205], v[104:105]
	v_cvt_pk_bf16_f32 v121, v197, v199
	v_pk_add_f32 v[104:105], v[126:127], v[104:105]
	v_cvt_pk_bf16_f32 v107, v186, v190
	v_pk_add_f32 v[104:105], v[206:207], v[104:105]
	v_cvt_pk_bf16_f32 v108, v192, v194
	v_pk_add_f32 v[110:111], v[128:129], v[104:105]
	v_cvt_pk_bf16_f32 v109, v196, v198
	v_pk_add_f32 v[132:133], v[132:133], v[110:111]
	s_waitcnt lgkmcnt(7)
	v_mfma_f32_16x16x32_bf16 v[26:29], v[208:211], v[118:121], v[26:29]
	v_cvt_pk_bf16_f32 v98, v201, v123
	v_cvt_pk_bf16_f32 v99, v203, v125
	v_cvt_pk_bf16_f32 v100, v205, v127
	v_mfma_f32_16x16x32_bf16 v[18:21], v[208:211], v[106:109], v[18:21]
	ds_read_b128 v[208:211], v131 offset:17472
	v_cvt_pk_bf16_f32 v101, v207, v129
	v_cvt_pk_bf16_f32 v102, v200, v122
	s_waitcnt lgkmcnt(7)
	v_mfma_f32_16x16x32_bf16 v[6:9], v[212:215], v[118:121], v[6:9]
	v_cvt_pk_bf16_f32 v103, v202, v124
	v_cvt_pk_bf16_f32 v104, v204, v126
	v_cvt_pk_bf16_f32 v105, v206, v128
	v_mfma_f32_16x16x32_bf16 v[2:5], v[212:215], v[106:109], v[2:5]
	ds_read_b128 v[212:215], v131 offset:19776
	v_lshl_add_u64 v[138:139], v[138:139], 0, s[46:47]
	v_lshl_add_u64 v[140:141], v[140:141], 0, s[46:47]
	s_waitcnt lgkmcnt(7)
	v_mfma_f32_16x16x32_bf16 v[14:17], v[216:219], v[118:121], v[14:17]
	s_cmpk_eq_i32 s18, 0x5c0
	v_mfma_f32_16x16x32_bf16 v[10:13], v[216:219], v[106:109], v[10:13]
	ds_read_b128 v[216:219], v131 offset:22080
	s_waitcnt lgkmcnt(7)
	v_mfma_f32_16x16x32_bf16 v[30:33], v[220:223], v[118:121], v[30:33]
	v_mfma_f32_16x16x32_bf16 v[22:25], v[220:223], v[106:109], v[22:25]
	ds_read_b128 v[220:223], v131 offset:24384
	s_waitcnt lgkmcnt(7)
	v_mfma_f32_16x16x32_bf16 v[38:41], v[224:227], v[118:121], v[38:41]
	v_mfma_f32_16x16x32_bf16 v[34:37], v[224:227], v[106:109], v[34:37]
	ds_read_b128 v[224:227], v131 offset:26688
	s_waitcnt lgkmcnt(7)
	v_mfma_f32_16x16x32_bf16 v[46:49], v[228:231], v[118:121], v[46:49]
	v_mfma_f32_16x16x32_bf16 v[42:45], v[228:231], v[106:109], v[42:45]
	ds_read_b128 v[228:231], v131 offset:28992
	s_waitcnt lgkmcnt(7)
	v_mfma_f32_16x16x32_bf16 v[54:57], v[244:247], v[118:121], v[54:57]
	v_mfma_f32_16x16x32_bf16 v[50:53], v[244:247], v[106:109], v[50:53]
	ds_read_b128 v[244:247], v131 offset:31296
	s_waitcnt lgkmcnt(7)
	v_mfma_f32_16x16x32_bf16 v[62:65], v[248:251], v[118:121], v[62:65]
	v_mfma_f32_16x16x32_bf16 v[58:61], v[248:251], v[106:109], v[58:61]
	ds_read_b128 v[248:251], v131 offset:33600
	s_waitcnt lgkmcnt(7)
	v_mfma_f32_16x16x32_bf16 v[26:29], v[208:211], v[98:101], v[26:29]
	v_mfma_f32_16x16x32_bf16 v[18:21], v[208:211], v[102:105], v[18:21]
	s_waitcnt lgkmcnt(6)
	v_mfma_f32_16x16x32_bf16 v[6:9], v[212:215], v[98:101], v[6:9]
	v_mfma_f32_16x16x32_bf16 v[2:5], v[212:215], v[102:105], v[2:5]
	s_waitcnt lgkmcnt(5)
	v_mfma_f32_16x16x32_bf16 v[14:17], v[216:219], v[98:101], v[14:17]
	v_mfma_f32_16x16x32_bf16 v[10:13], v[216:219], v[102:105], v[10:13]
	s_waitcnt lgkmcnt(4)
	v_mfma_f32_16x16x32_bf16 v[30:33], v[220:223], v[98:101], v[30:33]
	v_mfma_f32_16x16x32_bf16 v[22:25], v[220:223], v[102:105], v[22:25]
	s_waitcnt lgkmcnt(3)
	v_mfma_f32_16x16x32_bf16 v[38:41], v[224:227], v[98:101], v[38:41]
	v_mfma_f32_16x16x32_bf16 v[34:37], v[224:227], v[102:105], v[34:37]
	s_waitcnt lgkmcnt(2)
	v_mfma_f32_16x16x32_bf16 v[46:49], v[228:231], v[98:101], v[46:49]
	v_mfma_f32_16x16x32_bf16 v[42:45], v[228:231], v[102:105], v[42:45]
	s_waitcnt lgkmcnt(1)
	v_mfma_f32_16x16x32_bf16 v[54:57], v[244:247], v[98:101], v[54:57]
	v_mfma_f32_16x16x32_bf16 v[50:53], v[244:247], v[102:105], v[50:53]
	s_waitcnt lgkmcnt(0)
	v_mfma_f32_16x16x32_bf16 v[62:65], v[248:251], v[98:101], v[62:65]
	v_mfma_f32_16x16x32_bf16 v[58:61], v[248:251], v[102:105], v[58:61]
	s_cbranch_scc1 .LBB0_1105
	s_mov_b32 s19, s18
	s_branch .LBB0_1096
